# RWKV producer: R/K/V u16 loads prefetched one tile ahead across the barrier into freed B-buffer registers; B fragment load schedule rearranged
# speedup vs baseline: 1.0584x; 1.0014x over previous
.LBB0_375:
	s_waitcnt vmcnt(0)
	s_or_b64 exec, exec, s[34:35]
	s_setprio 0
	s_add_i32 s75, s75, s47
	s_cmpk_lt_i32 s75, 0x900
	s_barrier
	s_cbranch_scc0 .LBB0_528

.LBB0_401:
	s_or_b64 exec, exec, s[0:1]
	v_sub_u32_e32 v142, s19, v146
	s_and_saveexec_b64 s[0:1], s[6:7]
	s_xor_b64 s[0:1], exec, s[0:1]
	v_sub_u32_e32 v142, s19, v146
	v_add_u32_e32 v0, -9, v142
	v_mov_b32_e32 v1, v153
	v_lshl_add_u64 v[0:1], s[92:93], 0, v[0:1]
	s_andn2_saveexec_b64 s[0:1], s[0:1]
	v_lshl_add_u64 v[0:1], v[148:149], 0, s[92:93]
	s_or_b64 exec, exec, s[0:1]
	v_mad_u64_u32 v[4:5], s[0:1], v0, s95, v[168:169]
	v_mov_b32_e32 v0, v5
	v_mad_u64_u32 v[0:1], s[0:1], v1, s95, v[0:1]
	v_mov_b32_e32 v5, v0
	global_load_dwordx4 v[24:27], v[4:5], off
	global_load_dwordx4 v[16:19], v[4:5], off offset:64
	global_load_dwordx4 v[28:31], v[4:5], off offset:512
	global_load_dwordx4 v[20:23], v[4:5], off offset:576
	global_load_dwordx4 v[8:11], v[4:5], off offset:128
	global_load_dwordx4 v[0:3], v[4:5], off offset:192
	global_load_dwordx4 v[12:15], v[4:5], off offset:640
	s_nop 0
	global_load_dwordx4 v[4:7], v[4:5], off offset:704
	s_mov_b64 s[0:1], 0x1000
	v_lshl_add_u64 v[70:71], v[66:67], 0, s[0:1]
	v_lshl_add_u64 v[72:73], v[68:69], 0, s[0:1]
	s_mov_b64 s[0:1], 0x2000
	v_lshl_add_u64 v[74:75], v[66:67], 0, s[0:1]
	v_lshl_add_u64 v[76:77], v[68:69], 0, s[0:1]
	s_mov_b64 s[0:1], 0x3000
	v_lshl_add_u64 v[78:79], v[66:67], 0, s[0:1]
	v_lshl_add_u64 v[80:81], v[68:69], 0, s[0:1]
	s_mov_b64 s[0:1], 0x1040
	v_lshl_add_u64 v[82:83], v[66:67], 0, s[0:1]
	v_lshl_add_u64 v[84:85], v[68:69], 0, s[0:1]
	s_mov_b64 s[0:1], 0x2040
	v_lshl_add_u64 v[86:87], v[66:67], 0, s[0:1]
	v_lshl_add_u64 v[88:89], v[68:69], 0, s[0:1]
	s_mov_b64 s[0:1], 0x3040
	v_lshl_add_u64 v[90:91], v[66:67], 0, s[0:1]
	v_lshl_add_u64 v[92:93], v[68:69], 0, s[0:1]
	s_mov_b64 s[0:1], 0x1080
	v_lshl_add_u64 v[94:95], v[66:67], 0, s[0:1]
	v_lshl_add_u64 v[96:97], v[68:69], 0, s[0:1]
	s_mov_b64 s[0:1], 0x2080
	v_lshl_add_u64 v[98:99], v[66:67], 0, s[0:1]
	v_lshl_add_u64 v[100:101], v[68:69], 0, s[0:1]
	s_mov_b64 s[0:1], 0x3080
	v_lshl_add_u64 v[102:103], v[66:67], 0, s[0:1]
	v_lshl_add_u64 v[104:105], v[68:69], 0, s[0:1]
	s_mov_b64 s[0:1], 0x10c0
	v_lshl_add_u64 v[106:107], v[66:67], 0, s[0:1]
	v_lshl_add_u64 v[108:109], v[68:69], 0, s[0:1]
	s_mov_b64 s[0:1], 0x20c0
	s_add_i32 s28, s77, -1
	s_lshr_b32 s29, s19, 4
	s_lshl_b32 s30, s20, 2
	v_lshl_add_u64 v[110:111], v[66:67], 0, s[0:1]
	v_lshl_add_u64 v[112:113], v[68:69], 0, s[0:1]
	s_mov_b64 s[0:1], 0x30c0
	v_lshlrev_b32_e32 v32, 1, v36
	v_mov_b32_e32 v33, v153
	s_add_u32 s23, s92, s19
	v_lshl_add_u64 v[114:115], v[66:67], 0, s[0:1]
	v_lshl_add_u64 v[116:117], v[68:69], 0, s[0:1]
	v_lshl_add_u64 v[118:119], s[58:59], 0, v[32:33]
	s_mov_b32 s22, 2
	v_lshl_add_u64 v[120:121], v[166:167], 0, s[30:31]
	v_lshl_add_u64 v[122:123], v[164:165], 0, s[30:31]
	v_lshl_add_u64 v[124:125], s[92:93], 0, v[146:147]
	v_add_u32_e32 v126, s19, v202
	s_addc_u32 s24, s93, 0
	s_mov_b32 s25, 0
	s_mov_b64 s[90:91], 0
	s_mov_b64 s[18:19], 8
	v_lshlrev_b32_e32 v143, 1, v152
	s_mov_b32 s88, 2
	v_add_u32_e32 v64, s90, v126
	v_mov_b32_e32 v129, s19
	v_add_u32_e32 v128, -9, v64
	v_cndmask_b32_e64 v131, 0, v129, s[4:5]
	v_mov_b32_e32 v129, s18
	v_cndmask_b32_e64 v128, v128, v175, s[4:5]
	v_cndmask_b32_e64 v130, 0, v129, s[4:5]
	v_lshl_add_u64 v[220:221], v[130:131], 0, s[92:93]
	v_ashrrev_i32_e32 v129, 31, v128
	v_lshl_add_u64 v[128:129], v[220:221], 0, v[128:129]
	v_lshlrev_b64 v[128:129], 13, v[128:129]
	v_or_b32_e32 v128, v128, v143
	v_lshl_add_u64 v[222:223], s[60:61], 0, v[128:129]
	v_lshl_add_u64 v[224:225], s[62:63], 0, v[128:129]
	v_lshl_add_u64 v[226:227], s[64:65], 0, v[128:129]
	v_add_u32_e32 v128, -10, v64
	v_cndmask_b32_e64 v128, v128, v178, s[4:5]
	v_ashrrev_i32_e32 v129, 31, v128
	v_lshl_add_u64 v[128:129], v[220:221], 0, v[128:129]
	v_lshlrev_b64 v[128:129], 13, v[128:129]
	v_or_b32_e32 v128, v128, v143
	v_lshl_add_u64 v[228:229], s[60:61], 0, v[128:129]
	v_lshl_add_u64 v[230:231], s[62:63], 0, v[128:129]
	v_lshl_add_u64 v[232:233], s[64:65], 0, v[128:129]
	v_add_u32_e32 v128, -11, v64
	v_cndmask_b32_e64 v128, v128, v180, s[4:5]
	v_ashrrev_i32_e32 v129, 31, v128
	v_lshl_add_u64 v[128:129], v[220:221], 0, v[128:129]
	v_lshlrev_b64 v[128:129], 13, v[128:129]
	v_or_b32_e32 v128, v128, v143
	v_add_u32_e32 v64, -12, v64
	v_lshl_add_u64 v[234:235], s[60:61], 0, v[128:129]
	v_lshl_add_u64 v[236:237], s[62:63], 0, v[128:129]
	v_lshl_add_u64 v[238:239], s[64:65], 0, v[128:129]
	v_cndmask_b32_e64 v128, v64, v182, s[4:5]
	v_ashrrev_i32_e32 v129, 31, v128
	v_lshl_add_u64 v[128:129], v[220:221], 0, v[128:129]
	v_lshlrev_b64 v[128:129], 13, v[128:129]
	v_or_b32_e32 v128, v128, v143
	v_lshl_add_u64 v[242:243], s[64:65], 0, v[128:129]
	global_load_ushort v82, v[232:233], off
	global_load_ushort v83, v[238:239], off
	v_lshl_add_u64 v[220:221], s[60:61], 0, v[128:129]
	v_lshl_add_u64 v[240:241], s[62:63], 0, v[128:129]
	global_load_ushort v84, v[242:243], off
	global_load_ushort v85, v[232:233], off offset:32
	global_load_ushort v86, v[238:239], off offset:32
	global_load_ushort v87, v[242:243], off offset:32
	s_nop 0
	global_load_ushort v88, v[222:223], off
	global_load_ushort v89, v[224:225], off
	global_load_ushort v90, v[226:227], off
	global_load_ushort v91, v[228:229], off
	global_load_ushort v92, v[230:231], off
	global_load_ushort v93, v[234:235], off
	global_load_ushort v94, v[236:237], off
	global_load_ushort v95, v[220:221], off
	global_load_ushort v96, v[240:241], off
	global_load_ushort v97, v[222:223], off offset:32
	s_nop 0
	global_load_ushort v98, v[224:225], off offset:32
	s_nop 0
	global_load_ushort v99, v[226:227], off offset:32
	s_nop 0
	global_load_ushort v100, v[228:229], off offset:32
	global_load_ushort v101, v[230:231], off offset:32
	s_nop 0
	global_load_ushort v102, v[234:235], off offset:32
	global_load_ushort v103, v[236:237], off offset:32
	global_load_ushort v104, v[220:221], off offset:32
	global_load_ushort v105, v[240:241], off offset:32
	s_waitcnt lgkmcnt(0)
	s_barrier
	s_branch .LBB0_407
.LBB0_406:
	s_or_b64 exec, exec, s[16:17]
	s_waitcnt vmcnt(0)
	v_mad_u64_u32 v[4:5], s[0:1], v0, s95, v[168:169]
	v_mov_b32_e32 v0, v5
	v_mad_u64_u32 v[0:1], s[0:1], v1, s95, v[0:1]
	v_mov_b32_e32 v5, v0
	global_load_dwordx4 v[24:27], v[4:5], off
	global_load_dwordx4 v[16:19], v[4:5], off offset:64
	global_load_dwordx4 v[28:31], v[4:5], off offset:512
	global_load_dwordx4 v[20:23], v[4:5], off offset:576
	global_load_dwordx4 v[8:11], v[4:5], off offset:128
	global_load_dwordx4 v[0:3], v[4:5], off offset:192
	global_load_dwordx4 v[12:15], v[4:5], off offset:640
	s_nop 0
	global_load_dwordx4 v[4:7], v[4:5], off offset:704
	s_add_i32 s88, s88, 1
	s_add_u32 s90, s90, -8
	s_addc_u32 s91, s91, -1
	s_add_u32 s18, s18, 8
	s_addc_u32 s19, s19, 0
	s_add_i32 s22, s22, 2
	s_cmp_eq_u32 s25, s77
	s_mov_b32 s25, s72
	v_add_u32_e32 v64, s90, v126
	v_mov_b32_e32 v129, s19
	v_add_u32_e32 v128, -9, v64
	v_cndmask_b32_e64 v131, 0, v129, s[4:5]
	v_mov_b32_e32 v129, s18
	v_cndmask_b32_e64 v128, v128, v175, s[4:5]
	v_cndmask_b32_e64 v130, 0, v129, s[4:5]
	v_lshl_add_u64 v[220:221], v[130:131], 0, s[92:93]
	v_ashrrev_i32_e32 v129, 31, v128
	v_lshl_add_u64 v[128:129], v[220:221], 0, v[128:129]
	v_lshlrev_b64 v[128:129], 13, v[128:129]
	v_or_b32_e32 v128, v128, v143
	v_lshl_add_u64 v[222:223], s[60:61], 0, v[128:129]
	v_lshl_add_u64 v[224:225], s[62:63], 0, v[128:129]
	v_lshl_add_u64 v[226:227], s[64:65], 0, v[128:129]
	v_add_u32_e32 v128, -10, v64
	v_cndmask_b32_e64 v128, v128, v178, s[4:5]
	v_ashrrev_i32_e32 v129, 31, v128
	v_lshl_add_u64 v[128:129], v[220:221], 0, v[128:129]
	v_lshlrev_b64 v[128:129], 13, v[128:129]
	v_or_b32_e32 v128, v128, v143
	v_lshl_add_u64 v[228:229], s[60:61], 0, v[128:129]
	v_lshl_add_u64 v[230:231], s[62:63], 0, v[128:129]
	v_lshl_add_u64 v[232:233], s[64:65], 0, v[128:129]
	v_add_u32_e32 v128, -11, v64
	v_cndmask_b32_e64 v128, v128, v180, s[4:5]
	v_ashrrev_i32_e32 v129, 31, v128
	v_lshl_add_u64 v[128:129], v[220:221], 0, v[128:129]
	v_lshlrev_b64 v[128:129], 13, v[128:129]
	v_or_b32_e32 v128, v128, v143
	v_add_u32_e32 v64, -12, v64
	v_lshl_add_u64 v[234:235], s[60:61], 0, v[128:129]
	v_lshl_add_u64 v[236:237], s[62:63], 0, v[128:129]
	v_lshl_add_u64 v[238:239], s[64:65], 0, v[128:129]
	v_cndmask_b32_e64 v128, v64, v182, s[4:5]
	v_ashrrev_i32_e32 v129, 31, v128
	v_lshl_add_u64 v[128:129], v[220:221], 0, v[128:129]
	v_lshlrev_b64 v[128:129], 13, v[128:129]
	v_or_b32_e32 v128, v128, v143
	v_lshl_add_u64 v[242:243], s[64:65], 0, v[128:129]
	global_load_ushort v82, v[232:233], off
	global_load_ushort v83, v[238:239], off
	v_lshl_add_u64 v[220:221], s[60:61], 0, v[128:129]
	v_lshl_add_u64 v[240:241], s[62:63], 0, v[128:129]
	global_load_ushort v84, v[242:243], off
	global_load_ushort v85, v[232:233], off offset:32
	global_load_ushort v86, v[238:239], off offset:32
	global_load_ushort v87, v[242:243], off offset:32
	s_nop 0
	global_load_ushort v88, v[222:223], off
	global_load_ushort v89, v[224:225], off
	global_load_ushort v90, v[226:227], off
	global_load_ushort v91, v[228:229], off
	global_load_ushort v92, v[230:231], off
	global_load_ushort v93, v[234:235], off
	global_load_ushort v94, v[236:237], off
	global_load_ushort v95, v[220:221], off
	global_load_ushort v96, v[240:241], off
	global_load_ushort v97, v[222:223], off offset:32
	s_nop 0
	global_load_ushort v98, v[224:225], off offset:32
	s_nop 0
	global_load_ushort v99, v[226:227], off offset:32
	s_nop 0
	global_load_ushort v100, v[228:229], off offset:32
	global_load_ushort v101, v[230:231], off offset:32
	s_nop 0
	global_load_ushort v102, v[234:235], off offset:32
	global_load_ushort v103, v[236:237], off offset:32
	global_load_ushort v104, v[220:221], off offset:32
	global_load_ushort v105, v[240:241], off offset:32
	s_waitcnt lgkmcnt(0)
	s_barrier
	s_cbranch_scc1 .LBB0_375

.LBB0_437:
	s_add_i32 s72, s25, 1
	s_cmp_lt_u32 s72, s77
	s_cselect_b64 s[0:1], -1, 0
	s_cmp_ge_u32 s72, s77
	s_cbranch_scc1 .LBB0_439
	global_load_dwordx4 v[60:63], v[66:67], off
	global_load_dwordx4 v[52:55], v[68:69], off
	global_load_dwordx4 v[56:59], v[70:71], off
	global_load_dwordx4 v[44:47], v[72:73], off
	global_load_dwordx4 v[48:51], v[74:75], off
	global_load_dwordx4 v[36:39], v[76:77], off
	global_load_dwordx4 v[40:43], v[78:79], off
	global_load_dwordx4 v[32:35], v[80:81], off
	global_load_dwordx4 v[106:109], v[70:71], off offset:-4032
	global_load_dwordx4 v[110:113], v[72:73], off offset:-4032
	global_load_dwordx4 v[114:117], v[70:71], off offset:64
	global_load_dwordx4 v[248:251], v[72:73], off offset:64

.LBB0_510:
	s_andn2_b64 vcc, exec, s[0:1]
	s_cbranch_vccnz .LBB0_520
	s_waitcnt vmcnt(12)
	v_mov_b32_e32 v131, v82
	v_mov_b32_e32 v130, v83
	v_mov_b32_e32 v128, v84
	v_mov_b32_e32 v219, v85
	v_mov_b32_e32 v129, v86
	v_mov_b32_e32 v64, v87
	v_mov_b32_e32 v232, v88
	v_mov_b32_e32 v233, v89
	v_mov_b32_e32 v238, v90
	v_mov_b32_e32 v239, v91
	v_mov_b32_e32 v242, v92
	v_mov_b32_e32 v243, v93
	v_mov_b32_e32 v244, v94
	v_mov_b32_e32 v245, v95
	v_mov_b32_e32 v246, v96
	v_mov_b32_e32 v247, v97
	v_mov_b32_e32 v224, v98
	v_mov_b32_e32 v225, v99
	v_mov_b32_e32 v226, v100
	v_mov_b32_e32 v227, v101
	v_mov_b32_e32 v228, v102
	v_mov_b32_e32 v229, v103
	v_mov_b32_e32 v230, v104
	v_mov_b32_e32 v231, v105
	global_load_dwordx4 v[82:85], v[78:79], off offset:-4032
	global_load_dwordx4 v[86:89], v[80:81], off offset:-4032
	global_load_dwordx4 v[90:93], v[78:79], off offset:64
	global_load_dwordx4 v[94:97], v[80:81], off offset:64
	global_load_dwordx4 v[98:101], v[70:71], off offset:-3968
	global_load_dwordx4 v[102:105], v[72:73], off offset:-3968
	global_load_dwordx4 v[204:207], v[70:71], off offset:128
	global_load_dwordx4 v[208:211], v[72:73], off offset:128
	global_load_dwordx4 v[212:215], v[78:79], off offset:-3968
	s_waitcnt vmcnt(13)
	v_mfma_f32_16x16x32_bf16 v[60:63], v[24:27], v[60:63], 0
	v_mfma_f32_16x16x32_bf16 v[52:55], v[28:31], v[52:55], 0
	v_mfma_f32_16x16x32_bf16 v[56:59], v[24:27], v[56:59], 0
	v_mfma_f32_16x16x32_bf16 v[44:47], v[28:31], v[44:47], 0
	v_mfma_f32_16x16x32_bf16 v[48:51], v[24:27], v[48:51], 0
	v_mfma_f32_16x16x32_bf16 v[36:39], v[28:31], v[36:39], 0
	v_mfma_f32_16x16x32_bf16 v[24:27], v[24:27], v[40:43], 0
	v_mfma_f32_16x16x32_bf16 v[32:35], v[28:31], v[32:35], 0
	s_nop 1
	global_load_dwordx4 v[40:43], v[80:81], off offset:-3968
	global_load_dwordx4 v[28:31], v[78:79], off offset:128
	s_waitcnt vmcnt(11)
	v_mfma_f32_16x16x32_bf16 v[60:63], v[16:19], v[106:109], v[60:63]
	v_mfma_f32_16x16x32_bf16 v[52:55], v[20:23], v[110:113], v[52:55]
	v_mfma_f32_16x16x32_bf16 v[56:59], v[16:19], v[114:117], v[56:59]
	v_mfma_f32_16x16x32_bf16 v[44:47], v[20:23], v[248:251], v[44:47]
	s_waitcnt vmcnt(7)
	v_mfma_f32_16x16x32_bf16 v[48:51], v[16:19], v[82:85], v[48:51]
	v_mfma_f32_16x16x32_bf16 v[36:39], v[20:23], v[86:89], v[36:39]
	v_mfma_f32_16x16x32_bf16 v[24:27], v[16:19], v[90:93], v[24:27]
	v_mfma_f32_16x16x32_bf16 v[32:35], v[20:23], v[94:97], v[32:35]
	s_nop 1
	global_load_dwordx4 v[82:85], v[80:81], off offset:128
	global_load_dwordx4 v[86:89], v[70:71], off offset:-3904
	global_load_dwordx4 v[90:93], v[72:73], off offset:-3904
	global_load_dwordx4 v[94:97], v[70:71], off offset:192
	global_load_dwordx4 v[106:109], v[72:73], off offset:192
	global_load_dwordx4 v[110:113], v[78:79], off offset:-3904
	global_load_dwordx4 v[114:117], v[80:81], off offset:-3904
	global_load_dwordx4 v[248:251], v[78:79], off offset:192
	global_load_dwordx4 v[20:23], v[80:81], off offset:192
	s_waitcnt vmcnt(11)
	v_mfma_f32_16x16x32_bf16 v[60:63], v[8:11], v[98:101], v[60:63]
	v_mfma_f32_16x16x32_bf16 v[52:55], v[12:15], v[102:105], v[52:55]
	v_mfma_f32_16x16x32_bf16 v[56:59], v[8:11], v[204:207], v[56:59]
	v_mfma_f32_16x16x32_bf16 v[44:47], v[12:15], v[208:211], v[44:47]
	v_mfma_f32_16x16x32_bf16 v[48:51], v[8:11], v[212:215], v[48:51]
	s_waitcnt vmcnt(9)
	v_mfma_f32_16x16x32_bf16 v[36:39], v[12:15], v[40:43], v[36:39]
	v_mfma_f32_16x16x32_bf16 v[24:27], v[8:11], v[28:31], v[24:27]
	s_waitcnt vmcnt(8)
	v_mfma_f32_16x16x32_bf16 v[32:35], v[12:15], v[82:85], v[32:35]
	s_waitcnt vmcnt(7)
	v_mfma_f32_16x16x32_bf16 v[12:15], v[0:3], v[86:89], v[60:63]
	s_waitcnt vmcnt(6)
	v_mfma_f32_16x16x32_bf16 v[28:31], v[4:7], v[90:93], v[52:55]
	s_waitcnt vmcnt(5)
	v_mfma_f32_16x16x32_bf16 v[8:11], v[0:3], v[94:97], v[56:59]
	s_waitcnt vmcnt(4)
	v_mfma_f32_16x16x32_bf16 v[40:43], v[4:7], v[106:109], v[44:47]
	s_waitcnt vmcnt(3)
	v_mfma_f32_16x16x32_bf16 v[16:19], v[0:3], v[110:113], v[48:51]
	s_waitcnt vmcnt(2)
	v_mfma_f32_16x16x32_bf16 v[36:39], v[4:7], v[114:117], v[36:39]
	s_waitcnt vmcnt(1)
	v_mfma_f32_16x16x32_bf16 v[0:3], v[0:3], v[248:251], v[24:27]
	s_waitcnt vmcnt(0)
	v_mfma_f32_16x16x32_bf16 v[4:7], v[4:7], v[20:23], v[32:35]
	s_nop 7
	s_nop 3
	v_lshlrev_b32_e32 v233, 16, v233
	v_lshlrev_b32_e32 v232, 16, v232
	v_lshlrev_b32_e32 v22, 16, v243
	v_lshlrev_b32_e32 v23, 16, v239
	v_lshlrev_b32_e32 v20, 16, v245
	v_lshlrev_b32_e32 v44, 16, v244
	v_cndmask_b32_e64 v12, v16, v12, s[8:9]
	v_lshlrev_b32_e32 v57, 16, v242
	v_lshlrev_b32_e32 v45, 16, v247
	v_mul_f32_e32 v46, v127, v233
	v_lshlrev_b32_e32 v56, 16, v238
	v_lshlrev_b32_e32 v47, 16, v225
	v_cndmask_b32_e64 v0, v0, v8, s[8:9]
	v_add_f32_e32 v0, v135, v0
	v_mul_f32_e32 v0, 0xbfb8aa3b, v0
	s_nop 0
	v_cndmask_b32_e64 v27, v38, v30, s[8:9]
	v_cndmask_b32_e64 v16, v39, v31, s[8:9]
	v_cndmask_b32_e64 v28, v36, v28, s[8:9]
	s_nop 3
	v_cndmask_b32_e64 v31, v5, v41, s[8:9]
	v_add_f32_e32 v5, v134, v12
	v_add_f32_e32 v27, v136, v27
	v_cndmask_b32_e64 v29, v37, v29, s[8:9]
	v_cndmask_b32_e64 v8, v6, v42, s[8:9]
	v_add_f32_e32 v6, v136, v28
	v_add_f32_e32 v16, v136, v16
	v_mul_f32_e32 v5, 0xbfb8aa3b, v5
	v_mul_f32_e32 v27, 0xbfb8aa3b, v27
	v_add_f32_e32 v12, v136, v29
	v_mul_f32_e32 v6, 0xbfb8aa3b, v6
	v_mul_f32_e32 v16, 0xbfb8aa3b, v16
	v_exp_f32_e32 v5, v5
	v_exp_f32_e32 v27, v27
	v_mul_f32_e32 v12, 0xbfb8aa3b, v12
	v_exp_f32_e32 v6, v6
	v_exp_f32_e32 v16, v16
	v_exp_f32_e32 v0, v0
	v_cndmask_b32_e64 v4, v4, v40, s[8:9]
	v_exp_f32_e32 v12, v12
	v_add_f32_e32 v4, v137, v4
	v_mul_f32_e32 v4, 0xbfb8aa3b, v4
	v_add_f32_e32 v5, 1.0, v5
	v_add_f32_e32 v28, 1.0, v27
	v_exp_f32_e32 v4, v4
	v_add_f32_e32 v6, 1.0, v6
	v_add_f32_e32 v16, 1.0, v16
	v_add_f32_e32 v29, 1.0, v0
	v_rcp_f32_e32 v30, v5
	v_rcp_f32_e32 v5, v28
	v_add_f32_e32 v12, 1.0, v12
	v_rcp_f32_e32 v37, v6
	v_rcp_f32_e32 v0, v16
	v_rcp_f32_e32 v6, v29
	v_rcp_f32_e32 v27, v12
	v_add_f32_e32 v4, 1.0, v4
	v_add_f32_e32 v28, -1.0, v5
	v_rcp_f32_e32 v39, v4
	v_mul_f32_e32 v4, 0xbf1b4598, v30
	v_add_f32_e32 v29, -1.0, v0
	v_mul_f32_e32 v6, 0xbf1b4598, v6
	v_fma_f32 v28, v132, v28, 1.0
	v_lshlrev_b32_e32 v26, 16, v246
	v_add_f32_e32 v16, -1.0, v27
	v_mul_f32_e32 v4, 0x3fb8aa3b, v4
	v_fma_f32 v29, v132, v29, 1.0
	v_mul_f32_e32 v32, 0x3fb8aa3b, v6
	v_mul_f32_e32 v6, v28, v44
	v_mul_f32_e32 v21, v127, v26
	v_add_f32_e32 v12, -1.0, v37
	v_fma_f32 v16, v132, v16, 1.0
	v_exp_f32_e32 v40, v4
	v_mul_f32_e32 v4, v29, v26
	v_mul_f32_e32 v26, v6, v22
	v_cndmask_b32_e64 v7, v7, v43, s[8:9]
	v_fma_f32 v12, v132, v12, 1.0
	v_mul_f32_e32 v30, v16, v57
	v_fma_f32 v43, v133, v26, 0
	v_add_f32_e32 v26, v137, v31
	v_mul_f32_e32 v41, v12, v233
	v_mul_f32_e32 v16, v30, v23
	v_mul_f32_e32 v26, 0xbfb8aa3b, v26
	v_mul_f32_e32 v12, v41, v232
	v_fma_f32 v38, v133, v16, 0
	v_add_f32_e32 v16, -1.0, v39
	v_exp_f32_e32 v26, v26
	v_fma_f32 v36, v133, v12, 0
	v_lshlrev_b32_e32 v12, 16, v224
	v_fma_f32 v16, v139, v16, 1.0
	v_mul_f32_e32 v50, v16, v12
	v_add_f32_e32 v8, v137, v8
	v_mul_f32_e32 v48, v138, v12
	v_mul_f32_e32 v12, v50, v45
	v_mul_f32_e32 v8, 0xbfb8aa3b, v8
	v_fmac_f32_e32 v36, v140, v12
	v_add_f32_e32 v12, 1.0, v26
	v_exp_f32_e32 v8, v8
	v_rcp_f32_e32 v33, v12
	v_mul_f32_e32 v28, v4, v20
	v_mul_f32_e32 v24, v127, v44
	v_add_f32_e32 v8, 1.0, v8
	v_fma_f32 v44, v133, v28, 0
	v_add_f32_e32 v16, -1.0, v33
	v_rcp_f32_e32 v28, v8
	v_lshlrev_b32_e32 v12, 16, v227
	v_fma_f32 v16, v139, v16, 1.0
	v_add_f32_e32 v7, v137, v7
	v_exp_f32_e32 v42, v32
	v_lshlrev_b32_e32 v32, 16, v226
	v_mul_f32_e32 v35, v16, v12
	v_mul_f32_e32 v7, 0xbfb8aa3b, v7
	v_mul_f32_e32 v34, v138, v12
	v_mul_f32_e32 v12, v35, v32
	v_exp_f32_e32 v7, v7
	v_fmac_f32_e32 v38, v140, v12
	v_add_f32_e32 v12, -1.0, v28
	v_lshlrev_b32_e32 v8, 16, v229
	v_fma_f32 v12, v139, v12, 1.0
	v_lshlrev_b32_e32 v26, 16, v228
	v_mul_f32_e32 v31, v12, v8
	v_mul_f32_e32 v29, v138, v8
	v_mul_f32_e32 v8, v31, v26
	v_add_f32_e32 v7, 1.0, v7
	v_fmac_f32_e32 v43, v140, v8
	v_rcp_f32_e32 v8, v7
	v_mul_f32_e32 v49, v48, v48
	v_fmac_f32_e32 v49, v46, v46
	v_lshlrev_b32_e32 v16, 16, v231
	v_add_f32_e32 v54, -1.0, v8
	v_add_f32_dpp v49, v49, v49 quad_perm:[1,0,3,2] row_mask:0xf bank_mask:0xf bound_ctrl:1
	v_fma_f32 v54, v139, v54, 1.0
	v_lshlrev_b32_e32 v7, 16, v230
	v_add_f32_dpp v49, v49, v49 quad_perm:[2,3,0,1] row_mask:0xf bank_mask:0xf bound_ctrl:1
	v_mul_f32_e32 v12, v138, v16
	v_mul_f32_e32 v16, v54, v16
	v_add_f32_dpp v49, v49, v49 row_ror:4 row_mask:0xf bank_mask:0xf bound_ctrl:1
	v_add_f32_dpp v38, v38, v38 quad_perm:[1,0,3,2] row_mask:0xf bank_mask:0xf bound_ctrl:1
	v_mul_f32_e32 v54, v16, v7
	v_add_f32_dpp v49, v49, v49 row_ror:8 row_mask:0xf bank_mask:0xf bound_ctrl:1
	v_add_f32_dpp v36, v36, v36 quad_perm:[1,0,3,2] row_mask:0xf bank_mask:0xf bound_ctrl:1
	v_readlane_b32 s1, v49, 32
	v_add_f32_dpp v38, v38, v38 quad_perm:[2,3,0,1] row_mask:0xf bank_mask:0xf bound_ctrl:1
	v_mul_f32_e32 v52, v29, v29
	v_fmac_f32_e32 v44, v140, v54
	v_add_f32_dpp v36, v36, v36 quad_perm:[2,3,0,1] row_mask:0xf bank_mask:0xf bound_ctrl:1
	v_readlane_b32 s0, v49, 0
	v_mov_b32_e32 v54, s1
	v_readlane_b32 s1, v49, 48
	v_add_f32_dpp v38, v38, v38 row_ror:4 row_mask:0xf bank_mask:0xf bound_ctrl:1
	v_fmac_f32_e32 v52, v24, v24
	v_add_f32_dpp v36, v36, v36 row_ror:4 row_mask:0xf bank_mask:0xf bound_ctrl:1
	v_add_f32_e32 v54, s0, v54
	v_readlane_b32 s0, v49, 16
	v_mov_b32_e32 v49, s1
	v_add_f32_dpp v38, v38, v38 row_ror:8 row_mask:0xf bank_mask:0xf bound_ctrl:1
	v_add_f32_dpp v36, v36, v36 row_ror:8 row_mask:0xf bank_mask:0xf bound_ctrl:1
	v_add_f32_e32 v49, s0, v49
	v_readlane_b32 s3, v38, 0
	v_readlane_b32 s37, v38, 32
	v_readlane_b32 s36, v38, 16
	v_readlane_b32 s38, v38, 48
	v_add_f32_dpp v38, v52, v52 quad_perm:[1,0,3,2] row_mask:0xf bank_mask:0xf bound_ctrl:1
	v_add_f32_dpp v43, v43, v43 quad_perm:[1,0,3,2] row_mask:0xf bank_mask:0xf bound_ctrl:1
	v_readlane_b32 s43, v36, 0
	v_readlane_b32 s45, v36, 32
	v_readlane_b32 s44, v36, 16
	v_readlane_b32 s46, v36, 48
	v_cndmask_b32_e64 v36, v49, v54, s[10:11]
	v_add_f32_dpp v38, v38, v38 quad_perm:[2,3,0,1] row_mask:0xf bank_mask:0xf bound_ctrl:1
	v_add_f32_dpp v43, v43, v43 quad_perm:[2,3,0,1] row_mask:0xf bank_mask:0xf bound_ctrl:1
	v_mul_f32_e32 v53, v12, v12
	v_add_f32_dpp v38, v38, v38 row_ror:4 row_mask:0xf bank_mask:0xf bound_ctrl:1
	v_add_f32_dpp v43, v43, v43 row_ror:4 row_mask:0xf bank_mask:0xf bound_ctrl:1
	v_sqrt_f32_e32 v36, v36
	v_fmac_f32_e32 v53, v21, v21
	v_add_f32_dpp v38, v38, v38 row_ror:8 row_mask:0xf bank_mask:0xf bound_ctrl:1
	v_add_f32_dpp v43, v43, v43 row_ror:8 row_mask:0xf bank_mask:0xf bound_ctrl:1
	v_readlane_b32 s89, v38, 0
	v_readlane_b32 s74, v38, 32
	v_readlane_b32 s94, v38, 16
	v_readlane_b32 s2, v38, 48
	v_readlane_b32 s96, v43, 0
	v_readlane_b32 vcc_lo, v43, 32
	v_readlane_b32 s97, v43, 16
	v_readlane_b32 vcc_hi, v43, 48
	v_add_f32_dpp v38, v53, v53 quad_perm:[1,0,3,2] row_mask:0xf bank_mask:0xf bound_ctrl:1
	v_add_f32_dpp v43, v44, v44 quad_perm:[1,0,3,2] row_mask:0xf bank_mask:0xf bound_ctrl:1
	v_xor_b32_e32 v36, 0x80000000, v36
	v_add_f32_dpp v38, v38, v38 quad_perm:[2,3,0,1] row_mask:0xf bank_mask:0xf bound_ctrl:1
	v_add_f32_dpp v43, v43, v43 quad_perm:[2,3,0,1] row_mask:0xf bank_mask:0xf bound_ctrl:1
	v_min_f32_e32 v36, 0xab8cbccc, v36
	v_add_f32_dpp v38, v38, v38 row_ror:4 row_mask:0xf bank_mask:0xf bound_ctrl:1
	v_add_f32_dpp v43, v43, v43 row_ror:4 row_mask:0xf bank_mask:0xf bound_ctrl:1
	v_mul_f32_e32 v25, v127, v57
	v_add_f32_dpp v38, v38, v38 row_ror:8 row_mask:0xf bank_mask:0xf bound_ctrl:1
	v_add_f32_dpp v43, v43, v43 row_ror:8 row_mask:0xf bank_mask:0xf bound_ctrl:1
	v_readlane_b32 s26, v38, 0
	v_readlane_b32 s68, v38, 32
	v_readlane_b32 s27, v38, 16
	v_readlane_b32 s30, v38, 48
	v_readlane_b32 s16, v43, 0
	v_readlane_b32 s17, v43, 32
	v_readlane_b32 s20, v43, 16
	v_readlane_b32 s21, v43, 48
	v_and_or_b32 v38, s22, 2, v171
	v_rcp_f32_e32 v43, v36
	v_mul_f32_e32 v51, v34, v34
	v_lshl_or_b32 v36, v38, 3, v175
	v_fmac_f32_e32 v51, v25, v25
	v_mul_u32_u24_e32 v38, 0x600, v36
	v_lshl_or_b32 v44, v174, 2, v38
	v_add_f32_dpp v49, v51, v51 quad_perm:[1,0,3,2] row_mask:0xf bank_mask:0xf bound_ctrl:1
	v_mul_f32_e32 v46, v46, v43
	ds_write2_b32 v44, v40, v42 offset1:16
	v_add_f32_dpp v49, v49, v49 quad_perm:[2,3,0,1] row_mask:0xf bank_mask:0xf bound_ctrl:1
	v_mul_f32_e32 v40, v48, v43
	v_mul_f32_e64 v37, v37, -v46
	v_add_f32_dpp v49, v49, v49 row_ror:4 row_mask:0xf bank_mask:0xf bound_ctrl:1
	v_mul_f32_e64 v39, v39, -v40
	ds_write2_b32 v44, v46, v40 offset0:64 offset1:80
	v_add_f32_dpp v49, v49, v49 row_ror:8 row_mask:0xf bank_mask:0xf bound_ctrl:1
	ds_write2_b32 v44, v37, v39 offset0:128 offset1:144
	ds_write2_b32 v44, v41, v50 offset0:192 offset1:208
	v_add_u32_e32 v37, 0x400, v44
	s_movk_i32 s0, 0xfa04
	v_readlane_b32 s39, v49, 0
	v_readlane_b32 s41, v49, 32
	v_readlane_b32 s40, v49, 16
	v_readlane_b32 s42, v49, 48
	ds_write2_b32 v37, v232, v45 offset1:16
	ds_write2_b32 v37, v56, v47 offset0:64 offset1:80
	v_mad_i32_i24 v37, v36, s0, v38
	s_and_saveexec_b64 s[0:1], s[12:13]
	s_cbranch_execz .LBB0_513
	v_mov_b32_e32 v39, s45
	v_mov_b32_e32 v40, s46
	v_add_f32_e32 v39, s43, v39
	v_add_f32_e32 v40, s44, v40
	v_cndmask_b32_e64 v39, v40, v39, s[10:11]
	ds_write_b32 v37, v39 offset:57344

.Lp2_post:
	s_add_i32 s2, s22, -4
	v_and_or_b32 v220, s2, 2, v171
	v_lshl_or_b32 v221, v220, 11, v173
	v_mul_u32_u24_e32 v222, 0x3000, v220
	v_lshlrev_b32_e32 v223, 5, v220
	v_or_b32_e32 v222, v173, v222
	ds_read_b32 v230, v221 offset:49152
	ds_read_b32 v231, v221 offset:49408
	ds_read_b32 v232, v221 offset:49664
	ds_read_b32 v233, v221 offset:49920
	ds_read_b32 v234, v221 offset:50176
	ds_read_b32 v235, v221 offset:50432
	ds_read_b32 v236, v221 offset:50688
	ds_read_b32 v237, v221 offset:50944
	ds_read_b32 v238, v222 offset:1280
	ds_read_b32 v239, v222 offset:2816
	ds_read_b32 v240, v222 offset:4352
	ds_read_b32 v241, v222 offset:5888
	ds_read_b32 v242, v222 offset:7424
	ds_read_b32 v243, v222 offset:8960
	ds_read_b32 v244, v222 offset:10496
	ds_read_b32 v245, v222 offset:12032
	ds_read_b32 v64, v223 offset:57344
	ds_read_b32 v128, v223 offset:57348
	ds_read_b32 v129, v223 offset:57352
	ds_read_b32 v130, v223 offset:57356
	ds_read_b32 v131, v223 offset:57360
	ds_read_b32 v246, v223 offset:57364
	ds_read_b32 v247, v223 offset:57368
	ds_read_b32 v225, v223 offset:57372
	s_and_b64 vcc, exec, s[0:1]
	s_cbranch_vccz .Lp2_w0
	s_waitcnt vmcnt(12)
	s_branch .Lp2_w1
